# proj epilogue: leading half issues first row group before ALIGN barrier (plain path 2 stores, q/k path gain-load issue); on top of v81
# baseline (speedup 1.0000x reference)
;     __device__ __forceinline__ void operator()(const f32x4 (&acc)[2][2][4][2], const Unit& u, int wr, int wc, int fr, int fq) const {
;         const int row0 = u.pm * BM + wr * 64 + fr, colh = u.pn * BM + wc * 64 + 8 * fq;
;         if (u.pn < 4) {
;             const float* g = (u.pn < 2) ? gq : gk; const float sc = (u.pn < 2) ? 0.125f * 1.4426950408889634f : 1.0f;
;             f32x4 gv[2][2];
; #pragma unroll
;             for (int bj = 0; bj < 2; ++bj)
; #pragma unroll
;                 for (int n = 0; n < 2; ++n) gv[bj][n] = *(const PG8_GAS f32x4*)(g + 32 * bj + 8 * fq + 4 * n) * sc;
; #pragma unroll
;             for (int ai = 0; ai < 2; ++ai)
; #pragma unroll
;                 for (int m = 0; m < 4; ++m) {
;                     float ss = 0.f;
; #pragma unroll
;                     for (int bj = 0; bj < 2; ++bj)
; #pragma unroll
;                         for (int n = 0; n < 2; ++n) { const f32x4 x = acc[ai][bj][m][n]; ss += (x[0] * x[0] + x[1] * x[1]) + (x[2] * x[2] + x[3] * x[3]); }
;                     ss += __shfl_xor(ss, 16); ss += __shfl_xor(ss, 32);
;                     const float rstd = 1.0f / sqrtf(ss * (1.0f / 64.0f) + 1e-6f);
;                     bf16_t* p = O + (size_t)(row0 + ai * HALF + m * 16) * 3072 + colh;
; #pragma unroll
;                     for (int bj = 0; bj < 2; ++bj) {
;                         const f32x4 v0 = acc[ai][bj][m][0] * rstd * gv[bj][0], v1 = acc[ai][bj][m][1] * rstd * gv[bj][1];
;                         u32x4 w; w.x = cvtpk(v0[0], v0[1]); w.y = cvtpk(v0[2], v0[3]); w.z = cvtpk(v1[0], v1[1]); w.w = cvtpk(v1[2], v1[3]);
;                         __builtin_nontemporal_store(w, (PG8_GAS u32x4*)(p + 32 * bj));
;                     }
;                 }
;         } else {
; #pragma unroll
;             for (int ai = 0; ai < 2; ++ai)
; #pragma unroll
;                 for (int m = 0; m < 4; ++m) {
;                     bf16_t* p = O + (size_t)(row0 + ai * HALF + m * 16) * 3072 + colh;
; #pragma unroll
;                     for (int bj = 0; bj < 2; ++bj) {
;                         const f32x4 v0 = acc[ai][bj][m][0], v1 = acc[ai][bj][m][1];
;                         u32x4 w; w.x = cvtpk(v0[0], v0[1]); w.y = cvtpk(v0[2], v0[3]); w.z = cvtpk(v1[0], v1[1]); w.w = cvtpk(v1[2], v1[3]);
;                         __builtin_nontemporal_store(w, (PG8_GAS u32x4*)(p + 32 * bj));
;                     }
;                 }
.LBB0_257:
	v_lshl_add_u32 v177, s15, 8, v5
	v_lshl_or_b32 v0, s14, 8, v165
	s_mov_b64 s[6:7], -1
	s_cmp_lt_i32 s14, 4
	v_or_b32_e32 v176, 16, v177
	v_or_b32_e32 v175, 32, v177
	v_or_b32_e32 v174, 48, v177
	v_add_u32_e32 v173, 0x80, v177
	v_add_u32_e32 v172, 0x90, v177
	v_add_u32_e32 v169, 0xa0, v177
	v_add_u32_e32 v168, 0xb0, v177
	s_cbranch_scc1 .LBB0_259
	v_mov_b64_e32 v[148:149], s[8:9]
	v_mad_i64_i32 v[144:145], s[6:7], v177, s44, v[148:149]
	v_lshlrev_b64 v[150:151], 1, v[0:1]
	v_lshl_add_u64 v[152:153], v[144:145], 0, v[150:151]
	v_cvt_pk_bf16_f32 v144, v130, v131
	v_cvt_pk_bf16_f32 v145, v132, v133
	v_cvt_pk_bf16_f32 v146, v126, v127
	v_cvt_pk_bf16_f32 v147, v128, v129
	global_store_dwordx4 v[152:153], v[144:147], off nt
	s_nop 1
	v_cvt_pk_bf16_f32 v144, v122, v123
	v_cvt_pk_bf16_f32 v145, v124, v125
	v_cvt_pk_bf16_f32 v146, v118, v119
	v_cvt_pk_bf16_f32 v147, v120, v121
	global_store_dwordx4 v[152:153], v[144:147], off offset:64 nt
	s_nop 1
	s_cmp_eq_u64 s[78:79], 0
	s_cbranch_scc1 .Lproj_nb_pl
	s_barrier
.Lproj_nb_pl:
	v_mad_i64_i32 v[144:145], s[6:7], v176, s44, v[148:149]
	v_lshl_add_u64 v[152:153], v[144:145], 0, v[150:151]
	v_cvt_pk_bf16_f32 v144, v114, v115
	v_cvt_pk_bf16_f32 v145, v116, v117
	v_cvt_pk_bf16_f32 v146, v110, v111
	v_cvt_pk_bf16_f32 v147, v112, v113
	global_store_dwordx4 v[152:153], v[144:147], off nt
	s_nop 1
	v_cvt_pk_bf16_f32 v144, v106, v107
	v_cvt_pk_bf16_f32 v145, v108, v109
	v_cvt_pk_bf16_f32 v146, v102, v103
	v_cvt_pk_bf16_f32 v147, v104, v105
	global_store_dwordx4 v[152:153], v[144:147], off offset:64 nt
	s_nop 1
	v_mad_i64_i32 v[144:145], s[6:7], v175, s44, v[148:149]
	v_lshl_add_u64 v[152:153], v[144:145], 0, v[150:151]
	v_cvt_pk_bf16_f32 v144, v98, v99
	v_cvt_pk_bf16_f32 v145, v100, v101
	v_cvt_pk_bf16_f32 v146, v94, v95
	v_cvt_pk_bf16_f32 v147, v96, v97
	global_store_dwordx4 v[152:153], v[144:147], off nt
	s_nop 1
	v_cvt_pk_bf16_f32 v144, v90, v91
	v_cvt_pk_bf16_f32 v145, v92, v93
	v_cvt_pk_bf16_f32 v146, v86, v87
	v_cvt_pk_bf16_f32 v147, v88, v89
	global_store_dwordx4 v[152:153], v[144:147], off offset:64 nt
	s_nop 1
	v_mad_i64_i32 v[144:145], s[6:7], v174, s44, v[148:149]
	v_lshl_add_u64 v[152:153], v[144:145], 0, v[150:151]
	v_cvt_pk_bf16_f32 v144, v82, v83
	v_cvt_pk_bf16_f32 v145, v84, v85
	v_cvt_pk_bf16_f32 v146, v78, v79
	v_cvt_pk_bf16_f32 v147, v80, v81
	global_store_dwordx4 v[152:153], v[144:147], off nt
	s_nop 1
	v_cvt_pk_bf16_f32 v144, v74, v75
	v_cvt_pk_bf16_f32 v145, v76, v77
	v_cvt_pk_bf16_f32 v146, v70, v71
	v_cvt_pk_bf16_f32 v147, v72, v73
	global_store_dwordx4 v[152:153], v[144:147], off offset:64 nt
	s_nop 1
	v_mad_i64_i32 v[144:145], s[6:7], v173, s44, v[148:149]
	v_lshl_add_u64 v[152:153], v[144:145], 0, v[150:151]
	v_cvt_pk_bf16_f32 v144, v66, v67
	v_cvt_pk_bf16_f32 v145, v68, v69
	v_cvt_pk_bf16_f32 v146, v62, v63
	v_cvt_pk_bf16_f32 v147, v64, v65
	global_store_dwordx4 v[152:153], v[144:147], off nt
	s_nop 1
	v_cvt_pk_bf16_f32 v144, v58, v59
	v_cvt_pk_bf16_f32 v145, v60, v61
	v_cvt_pk_bf16_f32 v146, v54, v55
	v_cvt_pk_bf16_f32 v147, v56, v57
	global_store_dwordx4 v[152:153], v[144:147], off offset:64 nt
	s_nop 1
	v_mad_i64_i32 v[144:145], s[6:7], v172, s44, v[148:149]
	v_lshl_add_u64 v[152:153], v[144:145], 0, v[150:151]
	v_cvt_pk_bf16_f32 v144, v50, v51
	v_cvt_pk_bf16_f32 v145, v52, v53
	v_cvt_pk_bf16_f32 v146, v46, v47
	v_cvt_pk_bf16_f32 v147, v48, v49
	global_store_dwordx4 v[152:153], v[144:147], off nt
	s_nop 1
	v_cvt_pk_bf16_f32 v144, v42, v43
	v_cvt_pk_bf16_f32 v145, v44, v45
	v_cvt_pk_bf16_f32 v146, v38, v39
	v_cvt_pk_bf16_f32 v147, v40, v41
	global_store_dwordx4 v[152:153], v[144:147], off offset:64 nt
	s_nop 1
	v_mad_i64_i32 v[144:145], s[6:7], v169, s44, v[148:149]
	v_lshl_add_u64 v[152:153], v[144:145], 0, v[150:151]
	v_cvt_pk_bf16_f32 v144, v34, v35
	v_cvt_pk_bf16_f32 v145, v36, v37
	v_cvt_pk_bf16_f32 v146, v30, v31
	v_cvt_pk_bf16_f32 v147, v32, v33
	global_store_dwordx4 v[152:153], v[144:147], off nt
	s_nop 1
	v_cvt_pk_bf16_f32 v144, v26, v27
	v_cvt_pk_bf16_f32 v145, v28, v29
	v_cvt_pk_bf16_f32 v146, v22, v23
	v_cvt_pk_bf16_f32 v147, v24, v25
	global_store_dwordx4 v[152:153], v[144:147], off offset:64 nt
	s_nop 1
	v_mad_i64_i32 v[144:145], s[6:7], v168, s44, v[148:149]
	v_lshl_add_u64 v[160:161], v[144:145], 0, v[150:151]
	v_cvt_pk_bf16_f32 v144, v18, v19
	v_cvt_pk_bf16_f32 v145, v20, v21
	v_cvt_pk_bf16_f32 v146, v14, v15
	v_cvt_pk_bf16_f32 v147, v16, v17
	s_mov_b64 s[6:7], 0
	global_store_dwordx4 v[160:161], v[144:147], off nt
.LBB0_259:
	s_andn2_b64 vcc, exec, s[6:7]
	s_cbranch_vccnz .LBB0_261
	s_cmp_lt_i32 s14, 2
	s_cselect_b64 vcc, -1, 0
	s_and_b64 s[6:7], vcc, exec
	s_cselect_b32 s7, s11, s65
	s_cselect_b32 s6, s10, s64
	global_load_dwordx4 v[152:155], v167, s[6:7] offset:16
	global_load_dwordx4 v[144:147], v167, s[6:7]
	s_cmp_eq_u64 s[78:79], 0
	s_cbranch_scc1 .Lproj_nb_qk
	s_barrier
; #define PG8_GAS __attribute__((address_space(1)))
; __device__ __forceinline__ unsigned cvtpk(float lo, float hi) { f32x2 v = {lo, hi}; bf16x2_t b = __builtin_convertvector(v, bf16x2_t); return __builtin_bit_cast(unsigned, b); }
;     __device__ __forceinline__ void operator()(const f32x4 (&acc)[2][2][4][2], const Unit& u, int wr, int wc, int fr, int fq) const {
;     ...
;             const float* g = (u.pn < 2) ? gq : gk; const float sc = (u.pn < 2) ? 0.125f * 1.4426950408889634f : 1.0f;
;             f32x4 gv[2][2];
; #pragma unroll
;             for (int bj = 0; bj < 2; ++bj)
; #pragma unroll
;                 for (int n = 0; n < 2; ++n) gv[bj][n] = *(const PG8_GAS f32x4*)(g + 32 * bj + 8 * fq + 4 * n) * sc;
; #pragma unroll
;             for (int ai = 0; ai < 2; ++ai)
; #pragma unroll
;                 for (int m = 0; m < 4; ++m) {
;                     float ss = 0.f;
; #pragma unroll
;                     for (int bj = 0; bj < 2; ++bj)
; #pragma unroll
;                         for (int n = 0; n < 2; ++n) { const f32x4 x = acc[ai][bj][m][n]; ss += (x[0] * x[0] + x[1] * x[1]) + (x[2] * x[2] + x[3] * x[3]); }
;                     ss += __shfl_xor(ss, 16); ss += __shfl_xor(ss, 32);
;                     const float rstd = 1.0f / sqrtf(ss * (1.0f / 64.0f) + 1e-6f);
;                     bf16_t* p = O + (size_t)(row0 + ai * HALF + m * 16) * 3072 + colh;
; #pragma unroll
;                     for (int bj = 0; bj < 2; ++bj) {
;                         const f32x4 v0 = acc[ai][bj][m][0] * rstd * gv[bj][0], v1 = acc[ai][bj][m][1] * rstd * gv[bj][1];
;                         u32x4 w; w.x = cvtpk(v0[0], v0[1]); w.y = cvtpk(v0[2], v0[3]); w.z = cvtpk(v1[0], v1[1]); w.w = cvtpk(v1[2], v1[3]);
;                         __builtin_nontemporal_store(w, (PG8_GAS u32x4*)(p + 32 * bj));
;                     }
.Lproj_nb_qk:
	v_cndmask_b32_e32 v170, 1.0, v225, vcc
	v_cmp_lt_i32_e32 vcc, v218, v213
	v_pk_mul_f32 v[178:179], v[130:131], v[130:131]
	s_waitcnt vmcnt(0)
	v_pk_mul_f32 v[148:149], v[170:171], v[146:147] op_sel_hi:[0,1]
	v_pk_mul_f32 v[150:151], v[170:171], v[144:145] op_sel_hi:[0,1]
	v_pk_mul_f32 v[144:145], v[170:171], v[154:155] op_sel_hi:[0,1]
	v_pk_mul_f32 v[146:147], v[170:171], v[152:153] op_sel_hi:[0,1]
	global_load_dwordx4 v[160:163], v167, s[6:7] offset:144
	global_load_dwordx4 v[152:155], v167, s[6:7] offset:128
	s_waitcnt vmcnt(0)
	v_pk_mul_f32 v[156:157], v[170:171], v[154:155] op_sel_hi:[0,1]
	v_pk_mul_f32 v[154:155], v[170:171], v[160:161] op_sel_hi:[0,1]
	v_cndmask_b32_e32 v160, v212, v218, vcc
	v_cmp_lt_i32_e32 vcc, v219, v213
	v_pk_mul_f32 v[158:159], v[170:171], v[152:153] op_sel_hi:[0,1]
	v_pk_mul_f32 v[152:153], v[170:171], v[162:163] op_sel_hi:[0,1]
	v_lshlrev_b32_e32 v171, 2, v160
	v_cndmask_b32_e32 v160, v212, v219, vcc
	v_lshlrev_b32_e32 v170, 2, v160
	v_pk_mul_f32 v[160:161], v[132:133], v[132:133]
	v_ashrrev_i32_e32 v163, 31, v0
	v_pk_mov_b32 v[180:181], v[178:179], v[160:161] op_sel:[1,0]
	v_mov_b32_e32 v179, v161
	v_pk_add_f32 v[160:161], v[180:181], v[178:179]
	v_pk_mul_f32 v[178:179], v[128:129], v[128:129]
	v_pk_mul_f32 v[180:181], v[126:127], v[126:127]
	v_mov_b32_e32 v162, v0
	v_pk_mov_b32 v[182:183], v[180:181], v[178:179] op_sel:[1,0]
	v_mov_b32_e32 v181, v179
	v_pk_add_f32 v[178:179], v[182:183], v[180:181]
	v_mul_f32_e32 v0, v118, v118
	v_mul_f32_e32 v180, v119, v119
	v_pk_add_f32 v[160:161], v[160:161], v[160:161] op_sel:[0,1] op_sel_hi:[1,0]
	v_pk_add_f32 v[178:179], v[178:179], v[178:179] op_sel:[0,1] op_sel_hi:[1,0]
	v_mov_b32_e32 v161, v0
	v_mov_b32_e32 v179, v180
	v_mul_f32_e32 v0, v123, v123
	v_mul_f32_e32 v181, v120, v120
	v_pk_add_f32 v[160:161], v[160:161], v[178:179]
	v_pk_fma_f32 v[178:179], v[122:123], v[122:123], v[0:1] op_sel_hi:[1,1,0]
	v_mul_f32_e32 v0, v125, v125
	v_mul_f32_e32 v182, v121, v121
	v_mov_b32_e32 v179, v181
	v_pk_fma_f32 v[180:181], v[124:125], v[124:125], v[0:1] op_sel_hi:[1,1,0]
	v_lshlrev_b64 v[162:163], 1, v[162:163]
	v_mov_b32_e32 v181, v182
	v_pk_add_f32 v[178:179], v[178:179], v[180:181]
	s_nop 0
	v_pk_add_f32 v[160:161], v[160:161], v[178:179]
	s_nop 0
	v_add_f32_e32 v0, v160, v161
	ds_bpermute_b32 v160, v171, v0
	s_waitcnt lgkmcnt(0)
	v_add_f32_e32 v0, v0, v160
	ds_bpermute_b32 v160, v170, v0
	s_waitcnt lgkmcnt(0)
	v_add_f32_e32 v0, v0, v160
	v_fmamk_f32 v0, v0, 0x3c800000, v220
	v_cmp_gt_f32_e32 vcc, s45, v0
	v_mul_f32_e32 v160, 0x4f800000, v0
	s_nop 0
	v_cndmask_b32_e32 v0, v0, v160, vcc
	v_sqrt_f32_e32 v160, v0
	s_nop 0
	v_add_u32_e32 v161, -1, v160
	v_fma_f32 v178, -v161, v160, v0
	v_cmp_ge_f32_e64 s[6:7], 0, v178
	v_add_u32_e32 v178, 1, v160
	s_nop 0
	v_cndmask_b32_e64 v161, v160, v161, s[6:7]
	v_fma_f32 v160, -v178, v160, v0
	v_cmp_lt_f32_e64 s[6:7], 0, v160
	s_nop 1
	v_cndmask_b32_e64 v160, v161, v178, s[6:7]
	v_mul_f32_e32 v161, 0x37800000, v160
	v_cndmask_b32_e32 v160, v160, v161, vcc
	v_cmp_class_f32_e32 vcc, v0, v221
	s_nop 1
	v_cndmask_b32_e32 v0, v160, v0, vcc
	v_div_scale_f32 v160, s[6:7], v0, v0, 1.0
	v_rcp_f32_e32 v161, v160
	s_nop 0
	v_fma_f32 v178, -v160, v161, 1.0
	v_fmac_f32_e32 v161, v178, v161
	v_div_scale_f32 v178, vcc, 1.0, v0, 1.0
	v_mul_f32_e32 v179, v178, v161
	v_fma_f32 v180, -v160, v179, v178
	v_fmac_f32_e32 v179, v180, v161
	v_fma_f32 v160, -v160, v179, v178
	v_div_fmas_f32 v160, v160, v161, v179
	v_div_fixup_f32 v0, v160, v0, 1.0
	v_mov_b64_e32 v[160:161], s[8:9]
	v_pk_mul_f32 v[130:131], v[130:131], v[0:1] op_sel_hi:[1,0]
	v_pk_mul_f32 v[132:133], v[132:133], v[0:1] op_sel_hi:[1,0]
	v_pk_mul_f32 v[126:127], v[126:127], v[0:1] op_sel_hi:[1,0]
	v_pk_mul_f32 v[128:129], v[128:129], v[0:1] op_sel_hi:[1,0]
	v_mad_i64_i32 v[178:179], s[6:7], v177, s44, v[160:161]
	v_pk_mul_f32 v[132:133], v[148:149], v[132:133]
	v_pk_mul_f32 v[130:131], v[150:151], v[130:131]
	v_pk_mul_f32 v[180:181], v[144:145], v[128:129]
	v_pk_mul_f32 v[128:129], v[146:147], v[126:127]
	v_lshl_add_u64 v[178:179], v[178:179], 0, v[162:163]
	v_cvt_pk_bf16_f32 v126, v130, v131
	v_cvt_pk_bf16_f32 v127, v132, v133
	v_cvt_pk_bf16_f32 v128, v128, v129
	v_cvt_pk_bf16_f32 v129, v180, v181
	v_pk_mul_f32 v[122:123], v[122:123], v[0:1] op_sel_hi:[1,0]
	v_pk_mul_f32 v[124:125], v[124:125], v[0:1] op_sel_hi:[1,0]
	v_pk_mul_f32 v[118:119], v[118:119], v[0:1] op_sel_hi:[1,0]
	v_pk_mul_f32 v[120:121], v[120:121], v[0:1] op_sel_hi:[1,0]
	global_store_dwordx4 v[178:179], v[126:129], off nt
	v_pk_mul_f32 v[124:125], v[156:157], v[124:125]
	v_pk_mul_f32 v[122:123], v[158:159], v[122:123]
	v_pk_mul_f32 v[126:127], v[152:153], v[120:121]
	v_pk_mul_f32 v[120:121], v[154:155], v[118:119]
	v_cvt_pk_bf16_f32 v118, v122, v123
	v_cvt_pk_bf16_f32 v119, v124, v125
	v_cvt_pk_bf16_f32 v120, v120, v121
	v_cvt_pk_bf16_f32 v121, v126, v127
	global_store_dwordx4 v[178:179], v[118:121], off offset:64 nt
	v_mul_f32_e32 v0, v102, v102
	s_nop 0
	v_pk_mul_f32 v[118:119], v[116:117], v[116:117]
	v_pk_mul_f32 v[120:121], v[114:115], v[114:115]
	s_nop 0
	v_pk_mov_b32 v[122:123], v[120:121], v[118:119] op_sel:[1,0]
	v_mov_b32_e32 v121, v119
	v_pk_add_f32 v[118:119], v[122:123], v[120:121]
	v_pk_mul_f32 v[120:121], v[112:113], v[112:113]
	v_pk_mul_f32 v[122:123], v[110:111], v[110:111]
	v_pk_add_f32 v[118:119], v[118:119], v[118:119] op_sel:[0,1] op_sel_hi:[1,0]
	v_pk_mov_b32 v[124:125], v[122:123], v[120:121] op_sel:[1,0]
	v_mov_b32_e32 v123, v121
	v_pk_add_f32 v[120:121], v[124:125], v[122:123]
	v_mul_f32_e32 v122, v103, v103
	v_pk_add_f32 v[120:121], v[120:121], v[120:121] op_sel:[0,1] op_sel_hi:[1,0]
	v_mov_b32_e32 v119, v0
	v_mov_b32_e32 v121, v122
	v_mul_f32_e32 v0, v107, v107
	v_mul_f32_e32 v123, v104, v104
	v_pk_add_f32 v[118:119], v[118:119], v[120:121]
	v_pk_fma_f32 v[120:121], v[106:107], v[106:107], v[0:1] op_sel_hi:[1,1,0]
	v_mul_f32_e32 v0, v109, v109
	v_mul_f32_e32 v124, v105, v105
	v_mov_b32_e32 v121, v123
	v_pk_fma_f32 v[122:123], v[108:109], v[108:109], v[0:1] op_sel_hi:[1,1,0]
	s_nop 0
	v_mov_b32_e32 v123, v124
	v_pk_add_f32 v[120:121], v[120:121], v[122:123]
	s_nop 0
	v_pk_add_f32 v[118:119], v[118:119], v[120:121]
	s_nop 0
	v_add_f32_e32 v0, v118, v119
	ds_bpermute_b32 v118, v171, v0
	s_waitcnt lgkmcnt(0)
; #define PG8_GAS __attribute__((address_space(1)))
; __device__ __forceinline__ unsigned cvtpk(float lo, float hi) { f32x2 v = {lo, hi}; bf16x2_t b = __builtin_convertvector(v, bf16x2_t); return __builtin_bit_cast(unsigned, b); }
;     __device__ __forceinline__ void operator()(const f32x4 (&acc)[2][2][4][2], const Unit& u, int wr, int wc, int fr, int fq) const {
;     ...
;                 for (int m = 0; m < 4; ++m) {
;                     float ss = 0.f;
; #pragma unroll
;                     for (int bj = 0; bj < 2; ++bj)
; #pragma unroll
;                         for (int n = 0; n < 2; ++n) { const f32x4 x = acc[ai][bj][m][n]; ss += (x[0] * x[0] + x[1] * x[1]) + (x[2] * x[2] + x[3] * x[3]); }
;                     ss += __shfl_xor(ss, 16); ss += __shfl_xor(ss, 32);
;                     const float rstd = 1.0f / sqrtf(ss * (1.0f / 64.0f) + 1e-6f);
;                     bf16_t* p = O + (size_t)(row0 + ai * HALF + m * 16) * 3072 + colh;
; #pragma unroll
;                     for (int bj = 0; bj < 2; ++bj) {
;                         const f32x4 v0 = acc[ai][bj][m][0] * rstd * gv[bj][0], v1 = acc[ai][bj][m][1] * rstd * gv[bj][1];
;                         u32x4 w; w.x = cvtpk(v0[0], v0[1]); w.y = cvtpk(v0[2], v0[3]); w.z = cvtpk(v1[0], v1[1]); w.w = cvtpk(v1[2], v1[3]);
;                         __builtin_nontemporal_store(w, (PG8_GAS u32x4*)(p + 32 * bj));
;                     }
	v_add_f32_e32 v0, v0, v118
	ds_bpermute_b32 v118, v170, v0
	s_waitcnt lgkmcnt(0)
	v_add_f32_e32 v0, v0, v118
	v_fmamk_f32 v0, v0, 0x3c800000, v220
	v_cmp_gt_f32_e32 vcc, s45, v0
	v_mul_f32_e32 v118, 0x4f800000, v0
	s_nop 0
	v_cndmask_b32_e32 v0, v0, v118, vcc
	v_sqrt_f32_e32 v118, v0
	s_nop 0
	v_add_u32_e32 v119, -1, v118
	v_fma_f32 v120, -v119, v118, v0
	v_cmp_ge_f32_e64 s[6:7], 0, v120
	v_add_u32_e32 v120, 1, v118
	s_nop 0
	v_cndmask_b32_e64 v119, v118, v119, s[6:7]
	v_fma_f32 v118, -v120, v118, v0
	v_cmp_lt_f32_e64 s[6:7], 0, v118
	s_nop 1
	v_cndmask_b32_e64 v118, v119, v120, s[6:7]
	v_mul_f32_e32 v119, 0x37800000, v118
	v_cndmask_b32_e32 v118, v118, v119, vcc
	v_cmp_class_f32_e32 vcc, v0, v221
	s_nop 1
	v_cndmask_b32_e32 v0, v118, v0, vcc
	v_div_scale_f32 v118, s[6:7], v0, v0, 1.0
	v_rcp_f32_e32 v119, v118
	s_nop 0
	v_fma_f32 v120, -v118, v119, 1.0
	v_fmac_f32_e32 v119, v120, v119
	v_div_scale_f32 v120, vcc, 1.0, v0, 1.0
	v_mul_f32_e32 v121, v120, v119
	v_fma_f32 v122, -v118, v121, v120
	v_fmac_f32_e32 v121, v122, v119
	v_fma_f32 v118, -v118, v121, v120
	v_div_fmas_f32 v118, v118, v119, v121
	v_div_fixup_f32 v0, v118, v0, 1.0
	v_pk_mul_f32 v[114:115], v[114:115], v[0:1] op_sel_hi:[1,0]
	v_pk_mul_f32 v[116:117], v[116:117], v[0:1] op_sel_hi:[1,0]
	v_pk_mul_f32 v[110:111], v[110:111], v[0:1] op_sel_hi:[1,0]
	v_pk_mul_f32 v[112:113], v[112:113], v[0:1] op_sel_hi:[1,0]
	v_mad_i64_i32 v[118:119], s[6:7], v176, s44, v[160:161]
	v_pk_mul_f32 v[116:117], v[148:149], v[116:117]
	v_pk_mul_f32 v[114:115], v[150:151], v[114:115]
	v_pk_mul_f32 v[120:121], v[144:145], v[112:113]
	v_pk_mul_f32 v[112:113], v[146:147], v[110:111]
	v_lshl_add_u64 v[118:119], v[118:119], 0, v[162:163]
	v_cvt_pk_bf16_f32 v110, v114, v115
	v_cvt_pk_bf16_f32 v111, v116, v117
	v_cvt_pk_bf16_f32 v112, v112, v113
	v_cvt_pk_bf16_f32 v113, v120, v121
	v_pk_mul_f32 v[106:107], v[106:107], v[0:1] op_sel_hi:[1,0]
	v_pk_mul_f32 v[108:109], v[108:109], v[0:1] op_sel_hi:[1,0]
	v_pk_mul_f32 v[102:103], v[102:103], v[0:1] op_sel_hi:[1,0]
	v_pk_mul_f32 v[104:105], v[104:105], v[0:1] op_sel_hi:[1,0]
	global_store_dwordx4 v[118:119], v[110:113], off nt
	v_pk_mul_f32 v[108:109], v[156:157], v[108:109]
	v_pk_mul_f32 v[106:107], v[158:159], v[106:107]
	v_pk_mul_f32 v[110:111], v[152:153], v[104:105]
	v_pk_mul_f32 v[104:105], v[154:155], v[102:103]
	v_cvt_pk_bf16_f32 v102, v106, v107
	v_cvt_pk_bf16_f32 v103, v108, v109
	v_cvt_pk_bf16_f32 v104, v104, v105
	v_cvt_pk_bf16_f32 v105, v110, v111
	global_store_dwordx4 v[118:119], v[102:105], off offset:64 nt
	v_mul_f32_e32 v0, v86, v86
	s_nop 0
	v_pk_mul_f32 v[102:103], v[100:101], v[100:101]
	v_pk_mul_f32 v[104:105], v[98:99], v[98:99]
	s_nop 0
	v_pk_mov_b32 v[106:107], v[104:105], v[102:103] op_sel:[1,0]
	v_mov_b32_e32 v105, v103
	v_pk_add_f32 v[102:103], v[106:107], v[104:105]
	v_pk_mul_f32 v[104:105], v[96:97], v[96:97]
	v_pk_mul_f32 v[106:107], v[94:95], v[94:95]
	v_pk_add_f32 v[102:103], v[102:103], v[102:103] op_sel:[0,1] op_sel_hi:[1,0]
	v_pk_mov_b32 v[108:109], v[106:107], v[104:105] op_sel:[1,0]
	v_mov_b32_e32 v107, v105
	v_pk_add_f32 v[104:105], v[108:109], v[106:107]
	v_mul_f32_e32 v106, v87, v87
	v_pk_add_f32 v[104:105], v[104:105], v[104:105] op_sel:[0,1] op_sel_hi:[1,0]
	v_mov_b32_e32 v103, v0
	v_mov_b32_e32 v105, v106
	v_mul_f32_e32 v0, v91, v91
	v_mul_f32_e32 v107, v88, v88
	v_pk_add_f32 v[102:103], v[102:103], v[104:105]
	v_pk_fma_f32 v[104:105], v[90:91], v[90:91], v[0:1] op_sel_hi:[1,1,0]
	v_mul_f32_e32 v0, v93, v93
	v_mul_f32_e32 v108, v89, v89
	v_mov_b32_e32 v105, v107
	v_pk_fma_f32 v[106:107], v[92:93], v[92:93], v[0:1] op_sel_hi:[1,1,0]
	s_nop 0
	v_mov_b32_e32 v107, v108
	v_pk_add_f32 v[104:105], v[104:105], v[106:107]
	s_nop 0
	v_pk_add_f32 v[102:103], v[102:103], v[104:105]
	s_nop 0
	v_add_f32_e32 v0, v102, v103
	ds_bpermute_b32 v102, v171, v0
	s_waitcnt lgkmcnt(0)
	v_add_f32_e32 v0, v0, v102
	ds_bpermute_b32 v102, v170, v0
	s_waitcnt lgkmcnt(0)
	v_add_f32_e32 v0, v0, v102
	v_fmamk_f32 v0, v0, 0x3c800000, v220
	v_cmp_gt_f32_e32 vcc, s45, v0
	v_mul_f32_e32 v102, 0x4f800000, v0
	s_nop 0
	v_cndmask_b32_e32 v0, v0, v102, vcc
	v_sqrt_f32_e32 v102, v0
	s_nop 0
	v_add_u32_e32 v103, -1, v102
	v_fma_f32 v104, -v103, v102, v0
	v_cmp_ge_f32_e64 s[6:7], 0, v104
	v_add_u32_e32 v104, 1, v102
	s_nop 0
	v_cndmask_b32_e64 v103, v102, v103, s[6:7]
	v_fma_f32 v102, -v104, v102, v0
	v_cmp_lt_f32_e64 s[6:7], 0, v102
	s_nop 1
	v_cndmask_b32_e64 v102, v103, v104, s[6:7]
	v_mul_f32_e32 v103, 0x37800000, v102
	v_cndmask_b32_e32 v102, v102, v103, vcc
	v_cmp_class_f32_e32 vcc, v0, v221
	s_nop 1
	v_cndmask_b32_e32 v0, v102, v0, vcc
	v_div_scale_f32 v102, s[6:7], v0, v0, 1.0
	v_rcp_f32_e32 v103, v102
	s_nop 0
	v_fma_f32 v104, -v102, v103, 1.0
	v_fmac_f32_e32 v103, v104, v103
	v_div_scale_f32 v104, vcc, 1.0, v0, 1.0
	v_mul_f32_e32 v105, v104, v103
	v_fma_f32 v106, -v102, v105, v104
	v_fmac_f32_e32 v105, v106, v103
	v_fma_f32 v102, -v102, v105, v104
	v_div_fmas_f32 v102, v102, v103, v105
	v_div_fixup_f32 v0, v102, v0, 1.0
	v_pk_mul_f32 v[98:99], v[98:99], v[0:1] op_sel_hi:[1,0]
	v_pk_mul_f32 v[100:101], v[100:101], v[0:1] op_sel_hi:[1,0]
	v_pk_mul_f32 v[94:95], v[94:95], v[0:1] op_sel_hi:[1,0]
	v_pk_mul_f32 v[96:97], v[96:97], v[0:1] op_sel_hi:[1,0]
	v_mad_i64_i32 v[102:103], s[6:7], v175, s44, v[160:161]
	v_pk_mul_f32 v[100:101], v[148:149], v[100:101]
	v_pk_mul_f32 v[98:99], v[150:151], v[98:99]
	v_pk_mul_f32 v[104:105], v[144:145], v[96:97]
	v_pk_mul_f32 v[96:97], v[146:147], v[94:95]
	v_lshl_add_u64 v[102:103], v[102:103], 0, v[162:163]
	v_cvt_pk_bf16_f32 v94, v98, v99
	v_cvt_pk_bf16_f32 v95, v100, v101
	v_cvt_pk_bf16_f32 v96, v96, v97
; #define PG8_GAS __attribute__((address_space(1)))
; __device__ __forceinline__ unsigned cvtpk(float lo, float hi) { f32x2 v = {lo, hi}; bf16x2_t b = __builtin_convertvector(v, bf16x2_t); return __builtin_bit_cast(unsigned, b); }
;     __device__ __forceinline__ void operator()(const f32x4 (&acc)[2][2][4][2], const Unit& u, int wr, int wc, int fr, int fq) const {
;     ...
;                 for (int m = 0; m < 4; ++m) {
;                     float ss = 0.f;
; #pragma unroll
;                     for (int bj = 0; bj < 2; ++bj)
; #pragma unroll
;                         for (int n = 0; n < 2; ++n) { const f32x4 x = acc[ai][bj][m][n]; ss += (x[0] * x[0] + x[1] * x[1]) + (x[2] * x[2] + x[3] * x[3]); }
;                     ss += __shfl_xor(ss, 16); ss += __shfl_xor(ss, 32);
;                     const float rstd = 1.0f / sqrtf(ss * (1.0f / 64.0f) + 1e-6f);
;                     bf16_t* p = O + (size_t)(row0 + ai * HALF + m * 16) * 3072 + colh;
; #pragma unroll
;                     for (int bj = 0; bj < 2; ++bj) {
;                         const f32x4 v0 = acc[ai][bj][m][0] * rstd * gv[bj][0], v1 = acc[ai][bj][m][1] * rstd * gv[bj][1];
;                         u32x4 w; w.x = cvtpk(v0[0], v0[1]); w.y = cvtpk(v0[2], v0[3]); w.z = cvtpk(v1[0], v1[1]); w.w = cvtpk(v1[2], v1[3]);
;                         __builtin_nontemporal_store(w, (PG8_GAS u32x4*)(p + 32 * bj));
;                     }
	v_cvt_pk_bf16_f32 v97, v104, v105
	v_pk_mul_f32 v[90:91], v[90:91], v[0:1] op_sel_hi:[1,0]
	v_pk_mul_f32 v[92:93], v[92:93], v[0:1] op_sel_hi:[1,0]
	v_pk_mul_f32 v[86:87], v[86:87], v[0:1] op_sel_hi:[1,0]
	v_pk_mul_f32 v[88:89], v[88:89], v[0:1] op_sel_hi:[1,0]
	global_store_dwordx4 v[102:103], v[94:97], off nt
	v_pk_mul_f32 v[92:93], v[156:157], v[92:93]
	v_pk_mul_f32 v[90:91], v[158:159], v[90:91]
	v_pk_mul_f32 v[94:95], v[152:153], v[88:89]
	v_pk_mul_f32 v[88:89], v[154:155], v[86:87]
	v_cvt_pk_bf16_f32 v86, v90, v91
	v_cvt_pk_bf16_f32 v87, v92, v93
	v_cvt_pk_bf16_f32 v88, v88, v89
	v_cvt_pk_bf16_f32 v89, v94, v95
	global_store_dwordx4 v[102:103], v[86:89], off offset:64 nt
	v_mul_f32_e32 v0, v70, v70
	s_nop 0
	v_pk_mul_f32 v[86:87], v[84:85], v[84:85]
	v_pk_mul_f32 v[88:89], v[82:83], v[82:83]
	s_nop 0
	v_pk_mov_b32 v[90:91], v[88:89], v[86:87] op_sel:[1,0]
	v_mov_b32_e32 v89, v87
	v_pk_add_f32 v[86:87], v[90:91], v[88:89]
	v_pk_mul_f32 v[88:89], v[80:81], v[80:81]
	v_pk_mul_f32 v[90:91], v[78:79], v[78:79]
	v_pk_add_f32 v[86:87], v[86:87], v[86:87] op_sel:[0,1] op_sel_hi:[1,0]
	v_pk_mov_b32 v[92:93], v[90:91], v[88:89] op_sel:[1,0]
	v_mov_b32_e32 v91, v89
	v_pk_add_f32 v[88:89], v[92:93], v[90:91]
	v_mul_f32_e32 v90, v71, v71
	v_pk_add_f32 v[88:89], v[88:89], v[88:89] op_sel:[0,1] op_sel_hi:[1,0]
	v_mov_b32_e32 v87, v0
	v_mov_b32_e32 v89, v90
	v_mul_f32_e32 v0, v75, v75
	v_mul_f32_e32 v91, v72, v72
	v_pk_add_f32 v[86:87], v[86:87], v[88:89]
	v_pk_fma_f32 v[88:89], v[74:75], v[74:75], v[0:1] op_sel_hi:[1,1,0]
	v_mul_f32_e32 v0, v77, v77
	v_mul_f32_e32 v92, v73, v73
	v_mov_b32_e32 v89, v91
	v_pk_fma_f32 v[90:91], v[76:77], v[76:77], v[0:1] op_sel_hi:[1,1,0]
	s_nop 0
	v_mov_b32_e32 v91, v92
	v_pk_add_f32 v[88:89], v[88:89], v[90:91]
	s_nop 0
	v_pk_add_f32 v[86:87], v[86:87], v[88:89]
	s_nop 0
	v_add_f32_e32 v0, v86, v87
	ds_bpermute_b32 v86, v171, v0
	s_waitcnt lgkmcnt(0)
	v_add_f32_e32 v0, v0, v86
	ds_bpermute_b32 v86, v170, v0
	s_waitcnt lgkmcnt(0)
	v_add_f32_e32 v0, v0, v86
	v_fmamk_f32 v0, v0, 0x3c800000, v220
	v_cmp_gt_f32_e32 vcc, s45, v0
	v_mul_f32_e32 v86, 0x4f800000, v0
	s_nop 0
	v_cndmask_b32_e32 v0, v0, v86, vcc
	v_sqrt_f32_e32 v86, v0
	s_nop 0
	v_add_u32_e32 v87, -1, v86
	v_fma_f32 v88, -v87, v86, v0
	v_cmp_ge_f32_e64 s[6:7], 0, v88
	v_add_u32_e32 v88, 1, v86
	s_nop 0
	v_cndmask_b32_e64 v87, v86, v87, s[6:7]
	v_fma_f32 v86, -v88, v86, v0
	v_cmp_lt_f32_e64 s[6:7], 0, v86
	s_nop 1
	v_cndmask_b32_e64 v86, v87, v88, s[6:7]
	v_mul_f32_e32 v87, 0x37800000, v86
	v_cndmask_b32_e32 v86, v86, v87, vcc
	v_cmp_class_f32_e32 vcc, v0, v221
	s_nop 1
	v_cndmask_b32_e32 v0, v86, v0, vcc
	v_div_scale_f32 v86, s[6:7], v0, v0, 1.0
	v_rcp_f32_e32 v87, v86
	s_nop 0
	v_fma_f32 v88, -v86, v87, 1.0
	v_fmac_f32_e32 v87, v88, v87
	v_div_scale_f32 v88, vcc, 1.0, v0, 1.0
	v_mul_f32_e32 v89, v88, v87
	v_fma_f32 v90, -v86, v89, v88
	v_fmac_f32_e32 v89, v90, v87
	v_fma_f32 v86, -v86, v89, v88
	v_div_fmas_f32 v86, v86, v87, v89
	v_div_fixup_f32 v0, v86, v0, 1.0
	v_pk_mul_f32 v[82:83], v[82:83], v[0:1] op_sel_hi:[1,0]
	v_pk_mul_f32 v[84:85], v[84:85], v[0:1] op_sel_hi:[1,0]
	v_pk_mul_f32 v[78:79], v[78:79], v[0:1] op_sel_hi:[1,0]
	v_pk_mul_f32 v[80:81], v[80:81], v[0:1] op_sel_hi:[1,0]
	v_mad_i64_i32 v[86:87], s[6:7], v174, s44, v[160:161]
	v_pk_mul_f32 v[84:85], v[148:149], v[84:85]
	v_pk_mul_f32 v[82:83], v[150:151], v[82:83]
	v_pk_mul_f32 v[88:89], v[144:145], v[80:81]
	v_pk_mul_f32 v[80:81], v[146:147], v[78:79]
	v_lshl_add_u64 v[86:87], v[86:87], 0, v[162:163]
	v_cvt_pk_bf16_f32 v78, v82, v83
	v_cvt_pk_bf16_f32 v79, v84, v85
	v_cvt_pk_bf16_f32 v80, v80, v81
	v_cvt_pk_bf16_f32 v81, v88, v89
	v_pk_mul_f32 v[74:75], v[74:75], v[0:1] op_sel_hi:[1,0]
	v_pk_mul_f32 v[76:77], v[76:77], v[0:1] op_sel_hi:[1,0]
	v_pk_mul_f32 v[70:71], v[70:71], v[0:1] op_sel_hi:[1,0]
	v_pk_mul_f32 v[72:73], v[72:73], v[0:1] op_sel_hi:[1,0]
	global_store_dwordx4 v[86:87], v[78:81], off nt
	v_pk_mul_f32 v[76:77], v[156:157], v[76:77]
	v_pk_mul_f32 v[74:75], v[158:159], v[74:75]
	v_pk_mul_f32 v[78:79], v[152:153], v[72:73]
	v_pk_mul_f32 v[72:73], v[154:155], v[70:71]
	v_cvt_pk_bf16_f32 v70, v74, v75
	v_cvt_pk_bf16_f32 v71, v76, v77
	v_cvt_pk_bf16_f32 v72, v72, v73
	v_cvt_pk_bf16_f32 v73, v78, v79
	global_store_dwordx4 v[86:87], v[70:73], off offset:64 nt
	v_mul_f32_e32 v0, v54, v54
	s_nop 0
	v_pk_mul_f32 v[70:71], v[68:69], v[68:69]
	v_pk_mul_f32 v[72:73], v[66:67], v[66:67]
	s_nop 0
	v_pk_mov_b32 v[74:75], v[72:73], v[70:71] op_sel:[1,0]
	v_mov_b32_e32 v73, v71
	v_pk_add_f32 v[70:71], v[74:75], v[72:73]
	v_pk_mul_f32 v[72:73], v[64:65], v[64:65]
	v_pk_mul_f32 v[74:75], v[62:63], v[62:63]
	v_pk_add_f32 v[70:71], v[70:71], v[70:71] op_sel:[0,1] op_sel_hi:[1,0]
	v_pk_mov_b32 v[76:77], v[74:75], v[72:73] op_sel:[1,0]
	v_mov_b32_e32 v75, v73
	v_pk_add_f32 v[72:73], v[76:77], v[74:75]
	v_mul_f32_e32 v74, v55, v55
	v_pk_add_f32 v[72:73], v[72:73], v[72:73] op_sel:[0,1] op_sel_hi:[1,0]
	v_mov_b32_e32 v71, v0
	v_mov_b32_e32 v73, v74
	v_mul_f32_e32 v0, v59, v59
	v_mul_f32_e32 v75, v56, v56
	v_pk_add_f32 v[70:71], v[70:71], v[72:73]
	v_pk_fma_f32 v[72:73], v[58:59], v[58:59], v[0:1] op_sel_hi:[1,1,0]
	v_mul_f32_e32 v0, v61, v61
	v_mul_f32_e32 v76, v57, v57
	v_mov_b32_e32 v73, v75
	v_pk_fma_f32 v[74:75], v[60:61], v[60:61], v[0:1] op_sel_hi:[1,1,0]
	s_nop 0
	v_mov_b32_e32 v75, v76
	v_pk_add_f32 v[72:73], v[72:73], v[74:75]
	s_nop 0
	v_pk_add_f32 v[70:71], v[70:71], v[72:73]
	s_nop 0
	v_add_f32_e32 v0, v70, v71
	ds_bpermute_b32 v70, v171, v0
	s_waitcnt lgkmcnt(0)
	v_add_f32_e32 v0, v0, v70
	ds_bpermute_b32 v70, v170, v0
	s_waitcnt lgkmcnt(0)
; #define PG8_GAS __attribute__((address_space(1)))
; __device__ __forceinline__ unsigned cvtpk(float lo, float hi) { f32x2 v = {lo, hi}; bf16x2_t b = __builtin_convertvector(v, bf16x2_t); return __builtin_bit_cast(unsigned, b); }
;     __device__ __forceinline__ void operator()(const f32x4 (&acc)[2][2][4][2], const Unit& u, int wr, int wc, int fr, int fq) const {
;     ...
;                 for (int m = 0; m < 4; ++m) {
;                     float ss = 0.f;
; #pragma unroll
;                     for (int bj = 0; bj < 2; ++bj)
; #pragma unroll
;                         for (int n = 0; n < 2; ++n) { const f32x4 x = acc[ai][bj][m][n]; ss += (x[0] * x[0] + x[1] * x[1]) + (x[2] * x[2] + x[3] * x[3]); }
;                     ss += __shfl_xor(ss, 16); ss += __shfl_xor(ss, 32);
;                     const float rstd = 1.0f / sqrtf(ss * (1.0f / 64.0f) + 1e-6f);
;                     bf16_t* p = O + (size_t)(row0 + ai * HALF + m * 16) * 3072 + colh;
; #pragma unroll
;                     for (int bj = 0; bj < 2; ++bj) {
;                         const f32x4 v0 = acc[ai][bj][m][0] * rstd * gv[bj][0], v1 = acc[ai][bj][m][1] * rstd * gv[bj][1];
;                         u32x4 w; w.x = cvtpk(v0[0], v0[1]); w.y = cvtpk(v0[2], v0[3]); w.z = cvtpk(v1[0], v1[1]); w.w = cvtpk(v1[2], v1[3]);
;                         __builtin_nontemporal_store(w, (PG8_GAS u32x4*)(p + 32 * bj));
;                     }
	v_add_f32_e32 v0, v0, v70
	v_fmamk_f32 v0, v0, 0x3c800000, v220
	v_cmp_gt_f32_e32 vcc, s45, v0
	v_mul_f32_e32 v70, 0x4f800000, v0
	s_nop 0
	v_cndmask_b32_e32 v0, v0, v70, vcc
	v_sqrt_f32_e32 v70, v0
	s_nop 0
	v_add_u32_e32 v71, -1, v70
	v_fma_f32 v72, -v71, v70, v0
	v_cmp_ge_f32_e64 s[6:7], 0, v72
	v_add_u32_e32 v72, 1, v70
	s_nop 0
	v_cndmask_b32_e64 v71, v70, v71, s[6:7]
	v_fma_f32 v70, -v72, v70, v0
	v_cmp_lt_f32_e64 s[6:7], 0, v70
	s_nop 1
	v_cndmask_b32_e64 v70, v71, v72, s[6:7]
	v_mul_f32_e32 v71, 0x37800000, v70
	v_cndmask_b32_e32 v70, v70, v71, vcc
	v_cmp_class_f32_e32 vcc, v0, v221
	s_nop 1
	v_cndmask_b32_e32 v0, v70, v0, vcc
	v_div_scale_f32 v70, s[6:7], v0, v0, 1.0
	v_rcp_f32_e32 v71, v70
	s_nop 0
	v_fma_f32 v72, -v70, v71, 1.0
	v_fmac_f32_e32 v71, v72, v71
	v_div_scale_f32 v72, vcc, 1.0, v0, 1.0
	v_mul_f32_e32 v73, v72, v71
	v_fma_f32 v74, -v70, v73, v72
	v_fmac_f32_e32 v73, v74, v71
	v_fma_f32 v70, -v70, v73, v72
	v_div_fmas_f32 v70, v70, v71, v73
	v_div_fixup_f32 v0, v70, v0, 1.0
	v_pk_mul_f32 v[66:67], v[66:67], v[0:1] op_sel_hi:[1,0]
	v_pk_mul_f32 v[68:69], v[68:69], v[0:1] op_sel_hi:[1,0]
	v_pk_mul_f32 v[62:63], v[62:63], v[0:1] op_sel_hi:[1,0]
	v_pk_mul_f32 v[64:65], v[64:65], v[0:1] op_sel_hi:[1,0]
	v_mad_i64_i32 v[70:71], s[6:7], v173, s44, v[160:161]
	v_pk_mul_f32 v[68:69], v[148:149], v[68:69]
	v_pk_mul_f32 v[66:67], v[150:151], v[66:67]
	v_pk_mul_f32 v[72:73], v[144:145], v[64:65]
	v_pk_mul_f32 v[64:65], v[146:147], v[62:63]
	v_lshl_add_u64 v[70:71], v[70:71], 0, v[162:163]
	v_cvt_pk_bf16_f32 v62, v66, v67
	v_cvt_pk_bf16_f32 v63, v68, v69
	v_cvt_pk_bf16_f32 v64, v64, v65
	v_cvt_pk_bf16_f32 v65, v72, v73
	v_pk_mul_f32 v[58:59], v[58:59], v[0:1] op_sel_hi:[1,0]
	v_pk_mul_f32 v[60:61], v[60:61], v[0:1] op_sel_hi:[1,0]
	v_pk_mul_f32 v[54:55], v[54:55], v[0:1] op_sel_hi:[1,0]
	v_pk_mul_f32 v[56:57], v[56:57], v[0:1] op_sel_hi:[1,0]
	global_store_dwordx4 v[70:71], v[62:65], off nt
	v_pk_mul_f32 v[60:61], v[156:157], v[60:61]
	v_pk_mul_f32 v[58:59], v[158:159], v[58:59]
	v_pk_mul_f32 v[62:63], v[152:153], v[56:57]
	v_pk_mul_f32 v[56:57], v[154:155], v[54:55]
	v_cvt_pk_bf16_f32 v54, v58, v59
	v_cvt_pk_bf16_f32 v55, v60, v61
	v_cvt_pk_bf16_f32 v56, v56, v57
	v_cvt_pk_bf16_f32 v57, v62, v63
	global_store_dwordx4 v[70:71], v[54:57], off offset:64 nt
	v_mul_f32_e32 v0, v38, v38
	s_nop 0
	v_pk_mul_f32 v[54:55], v[52:53], v[52:53]
	v_pk_mul_f32 v[56:57], v[50:51], v[50:51]
	s_nop 0
	v_pk_mov_b32 v[58:59], v[56:57], v[54:55] op_sel:[1,0]
	v_mov_b32_e32 v57, v55
	v_pk_add_f32 v[54:55], v[58:59], v[56:57]
	v_pk_mul_f32 v[56:57], v[48:49], v[48:49]
	v_pk_mul_f32 v[58:59], v[46:47], v[46:47]
	v_pk_add_f32 v[54:55], v[54:55], v[54:55] op_sel:[0,1] op_sel_hi:[1,0]
	v_pk_mov_b32 v[60:61], v[58:59], v[56:57] op_sel:[1,0]
	v_mov_b32_e32 v59, v57
	v_pk_add_f32 v[56:57], v[60:61], v[58:59]
	v_mul_f32_e32 v58, v39, v39
	v_pk_add_f32 v[56:57], v[56:57], v[56:57] op_sel:[0,1] op_sel_hi:[1,0]
	v_mov_b32_e32 v55, v0
	v_mov_b32_e32 v57, v58
	v_mul_f32_e32 v0, v43, v43
	v_mul_f32_e32 v59, v40, v40
	v_pk_add_f32 v[54:55], v[54:55], v[56:57]
	v_pk_fma_f32 v[56:57], v[42:43], v[42:43], v[0:1] op_sel_hi:[1,1,0]
	v_mul_f32_e32 v0, v45, v45
	v_mul_f32_e32 v60, v41, v41
	v_mov_b32_e32 v57, v59
	v_pk_fma_f32 v[58:59], v[44:45], v[44:45], v[0:1] op_sel_hi:[1,1,0]
	s_nop 0
	v_mov_b32_e32 v59, v60
	v_pk_add_f32 v[56:57], v[56:57], v[58:59]
	s_nop 0
	v_pk_add_f32 v[54:55], v[54:55], v[56:57]
	s_nop 0
	v_add_f32_e32 v0, v54, v55
	ds_bpermute_b32 v54, v171, v0
	s_waitcnt lgkmcnt(0)
	v_add_f32_e32 v0, v0, v54
	ds_bpermute_b32 v54, v170, v0
	s_waitcnt lgkmcnt(0)
	v_add_f32_e32 v0, v0, v54
	v_fmamk_f32 v0, v0, 0x3c800000, v220
	v_cmp_gt_f32_e32 vcc, s45, v0
	v_mul_f32_e32 v54, 0x4f800000, v0
	s_nop 0
	v_cndmask_b32_e32 v0, v0, v54, vcc
	v_sqrt_f32_e32 v54, v0
	s_nop 0
	v_add_u32_e32 v55, -1, v54
	v_fma_f32 v56, -v55, v54, v0
	v_cmp_ge_f32_e64 s[6:7], 0, v56
	v_add_u32_e32 v56, 1, v54
	s_nop 0
	v_cndmask_b32_e64 v55, v54, v55, s[6:7]
	v_fma_f32 v54, -v56, v54, v0
	v_cmp_lt_f32_e64 s[6:7], 0, v54
	s_nop 1
	v_cndmask_b32_e64 v54, v55, v56, s[6:7]
	v_mul_f32_e32 v55, 0x37800000, v54
	v_cndmask_b32_e32 v54, v54, v55, vcc
	v_cmp_class_f32_e32 vcc, v0, v221
	s_nop 1
	v_cndmask_b32_e32 v0, v54, v0, vcc
	v_div_scale_f32 v54, s[6:7], v0, v0, 1.0
	v_rcp_f32_e32 v55, v54
	s_nop 0
	v_fma_f32 v56, -v54, v55, 1.0
	v_fmac_f32_e32 v55, v56, v55
	v_div_scale_f32 v56, vcc, 1.0, v0, 1.0
	v_mul_f32_e32 v57, v56, v55
	v_fma_f32 v58, -v54, v57, v56
	v_fmac_f32_e32 v57, v58, v55
	v_fma_f32 v54, -v54, v57, v56
	v_div_fmas_f32 v54, v54, v55, v57
	v_div_fixup_f32 v0, v54, v0, 1.0
	v_pk_mul_f32 v[50:51], v[50:51], v[0:1] op_sel_hi:[1,0]
	v_pk_mul_f32 v[52:53], v[52:53], v[0:1] op_sel_hi:[1,0]
	v_pk_mul_f32 v[46:47], v[46:47], v[0:1] op_sel_hi:[1,0]
	v_pk_mul_f32 v[48:49], v[48:49], v[0:1] op_sel_hi:[1,0]
	v_mad_i64_i32 v[54:55], s[6:7], v172, s44, v[160:161]
	v_pk_mul_f32 v[52:53], v[148:149], v[52:53]
	v_pk_mul_f32 v[50:51], v[150:151], v[50:51]
	v_pk_mul_f32 v[56:57], v[144:145], v[48:49]
	v_pk_mul_f32 v[48:49], v[146:147], v[46:47]
	v_lshl_add_u64 v[54:55], v[54:55], 0, v[162:163]
	v_cvt_pk_bf16_f32 v46, v50, v51
	v_cvt_pk_bf16_f32 v47, v52, v53
	v_cvt_pk_bf16_f32 v48, v48, v49
	v_cvt_pk_bf16_f32 v49, v56, v57
	v_pk_mul_f32 v[42:43], v[42:43], v[0:1] op_sel_hi:[1,0]
	v_pk_mul_f32 v[44:45], v[44:45], v[0:1] op_sel_hi:[1,0]
	v_pk_mul_f32 v[38:39], v[38:39], v[0:1] op_sel_hi:[1,0]
	v_pk_mul_f32 v[40:41], v[40:41], v[0:1] op_sel_hi:[1,0]
	global_store_dwordx4 v[54:55], v[46:49], off nt
	v_pk_mul_f32 v[44:45], v[156:157], v[44:45]
	v_pk_mul_f32 v[42:43], v[158:159], v[42:43]
; #define PG8_GAS __attribute__((address_space(1)))
; __device__ __forceinline__ unsigned cvtpk(float lo, float hi) { f32x2 v = {lo, hi}; bf16x2_t b = __builtin_convertvector(v, bf16x2_t); return __builtin_bit_cast(unsigned, b); }
;     __device__ __forceinline__ void operator()(const f32x4 (&acc)[2][2][4][2], const Unit& u, int wr, int wc, int fr, int fq) const {
;     ...
;                 for (int m = 0; m < 4; ++m) {
;                     float ss = 0.f;
; #pragma unroll
;                     for (int bj = 0; bj < 2; ++bj)
; #pragma unroll
;                         for (int n = 0; n < 2; ++n) { const f32x4 x = acc[ai][bj][m][n]; ss += (x[0] * x[0] + x[1] * x[1]) + (x[2] * x[2] + x[3] * x[3]); }
;                     ss += __shfl_xor(ss, 16); ss += __shfl_xor(ss, 32);
;                     const float rstd = 1.0f / sqrtf(ss * (1.0f / 64.0f) + 1e-6f);
;                     bf16_t* p = O + (size_t)(row0 + ai * HALF + m * 16) * 3072 + colh;
; #pragma unroll
;                     for (int bj = 0; bj < 2; ++bj) {
;                         const f32x4 v0 = acc[ai][bj][m][0] * rstd * gv[bj][0], v1 = acc[ai][bj][m][1] * rstd * gv[bj][1];
;                         u32x4 w; w.x = cvtpk(v0[0], v0[1]); w.y = cvtpk(v0[2], v0[3]); w.z = cvtpk(v1[0], v1[1]); w.w = cvtpk(v1[2], v1[3]);
;                         __builtin_nontemporal_store(w, (PG8_GAS u32x4*)(p + 32 * bj));
;                     }
	v_pk_mul_f32 v[46:47], v[152:153], v[40:41]
	v_pk_mul_f32 v[40:41], v[154:155], v[38:39]
	v_cvt_pk_bf16_f32 v38, v42, v43
	v_cvt_pk_bf16_f32 v39, v44, v45
	v_cvt_pk_bf16_f32 v40, v40, v41
	v_cvt_pk_bf16_f32 v41, v46, v47
	global_store_dwordx4 v[54:55], v[38:41], off offset:64 nt
	v_mul_f32_e32 v0, v22, v22
	s_nop 0
	v_pk_mul_f32 v[38:39], v[36:37], v[36:37]
	v_pk_mul_f32 v[40:41], v[34:35], v[34:35]
	s_nop 0
	v_pk_mov_b32 v[42:43], v[40:41], v[38:39] op_sel:[1,0]
	v_mov_b32_e32 v41, v39
	v_pk_add_f32 v[38:39], v[42:43], v[40:41]
	v_pk_mul_f32 v[40:41], v[32:33], v[32:33]
	v_pk_mul_f32 v[42:43], v[30:31], v[30:31]
	v_pk_add_f32 v[38:39], v[38:39], v[38:39] op_sel:[0,1] op_sel_hi:[1,0]
	v_pk_mov_b32 v[44:45], v[42:43], v[40:41] op_sel:[1,0]
	v_mov_b32_e32 v43, v41
	v_pk_add_f32 v[40:41], v[44:45], v[42:43]
	v_mul_f32_e32 v42, v23, v23
	v_pk_add_f32 v[40:41], v[40:41], v[40:41] op_sel:[0,1] op_sel_hi:[1,0]
	v_mov_b32_e32 v39, v0
	v_mov_b32_e32 v41, v42
	v_mul_f32_e32 v0, v27, v27
	v_mul_f32_e32 v43, v24, v24
	v_pk_add_f32 v[38:39], v[38:39], v[40:41]
	v_pk_fma_f32 v[40:41], v[26:27], v[26:27], v[0:1] op_sel_hi:[1,1,0]
	v_mul_f32_e32 v0, v29, v29
	v_mul_f32_e32 v44, v25, v25
	v_mov_b32_e32 v41, v43
	v_pk_fma_f32 v[42:43], v[28:29], v[28:29], v[0:1] op_sel_hi:[1,1,0]
	s_nop 0
	v_mov_b32_e32 v43, v44
	v_pk_add_f32 v[40:41], v[40:41], v[42:43]
	s_nop 0
	v_pk_add_f32 v[38:39], v[38:39], v[40:41]
	s_nop 0
	v_add_f32_e32 v0, v38, v39
	ds_bpermute_b32 v38, v171, v0
	s_waitcnt lgkmcnt(0)
	v_add_f32_e32 v0, v0, v38
	ds_bpermute_b32 v38, v170, v0
	s_waitcnt lgkmcnt(0)
	v_add_f32_e32 v0, v0, v38
	v_fmamk_f32 v0, v0, 0x3c800000, v220
	v_cmp_gt_f32_e32 vcc, s45, v0
	v_mul_f32_e32 v38, 0x4f800000, v0
	s_nop 0
	v_cndmask_b32_e32 v0, v0, v38, vcc
	v_sqrt_f32_e32 v38, v0
	s_nop 0
	v_add_u32_e32 v39, -1, v38
	v_fma_f32 v40, -v39, v38, v0
	v_cmp_ge_f32_e64 s[6:7], 0, v40
	v_add_u32_e32 v40, 1, v38
	s_nop 0
	v_cndmask_b32_e64 v39, v38, v39, s[6:7]
	v_fma_f32 v38, -v40, v38, v0
	v_cmp_lt_f32_e64 s[6:7], 0, v38
	s_nop 1
	v_cndmask_b32_e64 v38, v39, v40, s[6:7]
	v_mul_f32_e32 v39, 0x37800000, v38
	v_cndmask_b32_e32 v38, v38, v39, vcc
	v_cmp_class_f32_e32 vcc, v0, v221
	s_nop 1
	v_cndmask_b32_e32 v0, v38, v0, vcc
	v_div_scale_f32 v38, s[6:7], v0, v0, 1.0
	v_rcp_f32_e32 v39, v38
	s_nop 0
	v_fma_f32 v40, -v38, v39, 1.0
	v_fmac_f32_e32 v39, v40, v39
	v_div_scale_f32 v40, vcc, 1.0, v0, 1.0
	v_mul_f32_e32 v41, v40, v39
	v_fma_f32 v42, -v38, v41, v40
	v_fmac_f32_e32 v41, v42, v39
	v_fma_f32 v38, -v38, v41, v40
	v_div_fmas_f32 v38, v38, v39, v41
	v_div_fixup_f32 v0, v38, v0, 1.0
	v_pk_mul_f32 v[34:35], v[34:35], v[0:1] op_sel_hi:[1,0]
	v_pk_mul_f32 v[36:37], v[36:37], v[0:1] op_sel_hi:[1,0]
	v_pk_mul_f32 v[30:31], v[30:31], v[0:1] op_sel_hi:[1,0]
	v_pk_mul_f32 v[32:33], v[32:33], v[0:1] op_sel_hi:[1,0]
	v_mad_i64_i32 v[38:39], s[6:7], v169, s44, v[160:161]
	v_pk_mul_f32 v[36:37], v[148:149], v[36:37]
	v_pk_mul_f32 v[34:35], v[150:151], v[34:35]
	v_pk_mul_f32 v[40:41], v[144:145], v[32:33]
	v_pk_mul_f32 v[32:33], v[146:147], v[30:31]
	v_lshl_add_u64 v[38:39], v[38:39], 0, v[162:163]
	v_cvt_pk_bf16_f32 v30, v34, v35
	v_cvt_pk_bf16_f32 v31, v36, v37
	v_cvt_pk_bf16_f32 v32, v32, v33
	v_cvt_pk_bf16_f32 v33, v40, v41
	v_pk_mul_f32 v[26:27], v[26:27], v[0:1] op_sel_hi:[1,0]
	v_pk_mul_f32 v[28:29], v[28:29], v[0:1] op_sel_hi:[1,0]
	v_pk_mul_f32 v[22:23], v[22:23], v[0:1] op_sel_hi:[1,0]
	v_pk_mul_f32 v[24:25], v[24:25], v[0:1] op_sel_hi:[1,0]
	global_store_dwordx4 v[38:39], v[30:33], off nt
	v_pk_mul_f32 v[28:29], v[156:157], v[28:29]
	v_pk_mul_f32 v[26:27], v[158:159], v[26:27]
	v_pk_mul_f32 v[30:31], v[152:153], v[24:25]
	v_pk_mul_f32 v[24:25], v[154:155], v[22:23]
	v_cvt_pk_bf16_f32 v22, v26, v27
	v_cvt_pk_bf16_f32 v23, v28, v29
	v_cvt_pk_bf16_f32 v24, v24, v25
	v_cvt_pk_bf16_f32 v25, v30, v31
	global_store_dwordx4 v[38:39], v[22:25], off offset:64 nt
	v_mul_f32_e32 v0, v6, v6
	s_nop 0
	v_pk_mul_f32 v[22:23], v[20:21], v[20:21]
	v_pk_mul_f32 v[24:25], v[18:19], v[18:19]
	s_nop 0
	v_pk_mov_b32 v[26:27], v[24:25], v[22:23] op_sel:[1,0]
	v_mov_b32_e32 v25, v23
	v_pk_add_f32 v[22:23], v[26:27], v[24:25]
	v_pk_mul_f32 v[24:25], v[16:17], v[16:17]
	v_pk_mul_f32 v[26:27], v[14:15], v[14:15]
	v_pk_add_f32 v[22:23], v[22:23], v[22:23] op_sel:[0,1] op_sel_hi:[1,0]
	v_pk_mov_b32 v[28:29], v[26:27], v[24:25] op_sel:[1,0]
	v_mov_b32_e32 v27, v25
	v_pk_add_f32 v[24:25], v[28:29], v[26:27]
	v_mul_f32_e32 v26, v7, v7
	v_pk_add_f32 v[24:25], v[24:25], v[24:25] op_sel:[0,1] op_sel_hi:[1,0]
	v_mov_b32_e32 v23, v0
	v_mov_b32_e32 v25, v26
	v_mul_f32_e32 v0, v11, v11
	v_mul_f32_e32 v27, v8, v8
	v_pk_add_f32 v[22:23], v[22:23], v[24:25]
	v_pk_fma_f32 v[24:25], v[10:11], v[10:11], v[0:1] op_sel_hi:[1,1,0]
	v_mul_f32_e32 v0, v13, v13
	v_mul_f32_e32 v28, v9, v9
	v_mov_b32_e32 v25, v27
	v_pk_fma_f32 v[26:27], v[12:13], v[12:13], v[0:1] op_sel_hi:[1,1,0]
	s_nop 0
	v_mov_b32_e32 v27, v28
	v_pk_add_f32 v[24:25], v[24:25], v[26:27]
	s_nop 0
	v_pk_add_f32 v[22:23], v[22:23], v[24:25]
	s_nop 0
	v_add_f32_e32 v0, v22, v23
	ds_bpermute_b32 v22, v171, v0
	s_waitcnt lgkmcnt(0)
; #define PG8_GAS __attribute__((address_space(1)))
; __device__ __forceinline__ unsigned cvtpk(float lo, float hi) { f32x2 v = {lo, hi}; bf16x2_t b = __builtin_convertvector(v, bf16x2_t); return __builtin_bit_cast(unsigned, b); }
;     __device__ __forceinline__ void operator()(const f32x4 (&acc)[2][2][4][2], const Unit& u, int wr, int wc, int fr, int fq) const {
;     ...
;                 for (int m = 0; m < 4; ++m) {
;                     float ss = 0.f;
; #pragma unroll
;                     for (int bj = 0; bj < 2; ++bj)
; #pragma unroll
;                         for (int n = 0; n < 2; ++n) { const f32x4 x = acc[ai][bj][m][n]; ss += (x[0] * x[0] + x[1] * x[1]) + (x[2] * x[2] + x[3] * x[3]); }
;                     ss += __shfl_xor(ss, 16); ss += __shfl_xor(ss, 32);
;                     const float rstd = 1.0f / sqrtf(ss * (1.0f / 64.0f) + 1e-6f);
;                     bf16_t* p = O + (size_t)(row0 + ai * HALF + m * 16) * 3072 + colh;
; #pragma unroll
;                     for (int bj = 0; bj < 2; ++bj) {
;                         const f32x4 v0 = acc[ai][bj][m][0] * rstd * gv[bj][0], v1 = acc[ai][bj][m][1] * rstd * gv[bj][1];
;                         u32x4 w; w.x = cvtpk(v0[0], v0[1]); w.y = cvtpk(v0[2], v0[3]); w.z = cvtpk(v1[0], v1[1]); w.w = cvtpk(v1[2], v1[3]);
;                         __builtin_nontemporal_store(w, (PG8_GAS u32x4*)(p + 32 * bj));
;                     }
	v_add_f32_e32 v0, v0, v22
	ds_bpermute_b32 v22, v170, v0
	s_waitcnt lgkmcnt(0)
	v_add_f32_e32 v0, v0, v22
	v_fmamk_f32 v0, v0, 0x3c800000, v220
	v_cmp_gt_f32_e32 vcc, s45, v0
	v_mul_f32_e32 v22, 0x4f800000, v0
	s_nop 0
	v_cndmask_b32_e32 v0, v0, v22, vcc
	v_sqrt_f32_e32 v22, v0
	s_nop 0
	v_add_u32_e32 v23, -1, v22
	v_fma_f32 v24, -v23, v22, v0
	v_cmp_ge_f32_e64 s[6:7], 0, v24
	v_add_u32_e32 v24, 1, v22
	s_nop 0
	v_cndmask_b32_e64 v23, v22, v23, s[6:7]
	v_fma_f32 v22, -v24, v22, v0
	v_cmp_lt_f32_e64 s[6:7], 0, v22
	s_nop 1
	v_cndmask_b32_e64 v22, v23, v24, s[6:7]
	v_mul_f32_e32 v23, 0x37800000, v22
	v_cndmask_b32_e32 v22, v22, v23, vcc
	v_cmp_class_f32_e32 vcc, v0, v221
	s_nop 1
	v_cndmask_b32_e32 v0, v22, v0, vcc
	v_div_scale_f32 v22, s[6:7], v0, v0, 1.0
	v_rcp_f32_e32 v23, v22
	s_nop 0
	v_fma_f32 v24, -v22, v23, 1.0
	v_fmac_f32_e32 v23, v24, v23
	v_div_scale_f32 v24, vcc, 1.0, v0, 1.0
	v_mul_f32_e32 v25, v24, v23
	v_fma_f32 v26, -v22, v25, v24
	v_fmac_f32_e32 v25, v26, v23
	v_fma_f32 v22, -v22, v25, v24
	v_div_fmas_f32 v22, v22, v23, v25
	v_div_fixup_f32 v0, v22, v0, 1.0
	v_mad_i64_i32 v[22:23], s[6:7], v168, s44, v[160:161]
	v_pk_mul_f32 v[18:19], v[18:19], v[0:1] op_sel_hi:[1,0]
	v_pk_mul_f32 v[20:21], v[20:21], v[0:1] op_sel_hi:[1,0]
	v_pk_mul_f32 v[14:15], v[14:15], v[0:1] op_sel_hi:[1,0]
	v_pk_mul_f32 v[16:17], v[16:17], v[0:1] op_sel_hi:[1,0]
	v_lshl_add_u64 v[160:161], v[22:23], 0, v[162:163]
	v_pk_mul_f32 v[20:21], v[148:149], v[20:21]
	v_pk_mul_f32 v[18:19], v[150:151], v[18:19]
	v_pk_mul_f32 v[22:23], v[144:145], v[16:17]
	v_pk_mul_f32 v[16:17], v[146:147], v[14:15]
	v_pk_mul_f32 v[10:11], v[10:11], v[0:1] op_sel_hi:[1,0]
	v_pk_mul_f32 v[12:13], v[12:13], v[0:1] op_sel_hi:[1,0]
	v_pk_mul_f32 v[6:7], v[6:7], v[0:1] op_sel_hi:[1,0]
	v_pk_mul_f32 v[8:9], v[8:9], v[0:1] op_sel_hi:[1,0]
	v_cvt_pk_bf16_f32 v14, v18, v19
	v_cvt_pk_bf16_f32 v15, v20, v21
	v_cvt_pk_bf16_f32 v16, v16, v17
	v_cvt_pk_bf16_f32 v17, v22, v23
	v_pk_mul_f32 v[12:13], v[156:157], v[12:13]
	v_pk_mul_f32 v[10:11], v[158:159], v[10:11]
	v_pk_mul_f32 v[8:9], v[152:153], v[8:9]
	v_pk_mul_f32 v[6:7], v[154:155], v[6:7]
	global_store_dwordx4 v[160:161], v[14:17], off nt
